# S5 carry scan chunk loop hand-written: two-block prefetch of local states, lean address stepping; arithmetic identical to baseline
# speedup vs baseline: 1.0075x; 1.0075x over previous
; __device__ __forceinline__ void phase_scan(const Frame& F, const Params& P, int l) {
;     ...
;         const int g = ww >> 3, b = (ww >> 1) & 3, d = ww & 1, p = F.lane; const int gi = (l * 2 + d) * 32 + g;
;         const float lr = lam_re[gi * 64 + p], li = lam_im[gi * 64 + p], dt = expf(log_dt[gi]);
;         const float mag = expf(32.0f * lr * dt); float sn, cs; sincosf(32.0f * li * dt, &sn, &cs);
;         const float aLr = mag * cs, aLi = mag * sn;
;         const int ctxb = (NLAT + 256 * b) / 32, latb = 256 * b;
;         float cr = 0.f, ci = 0.f;
;         auto chunk_of = [&](int j) -> int { return (j < 8) ? (ctxb + (d ? 7 - j : j)) : (latb + (d ? 255 - (j - 8) : (j - 8))); };
;         float sr[8], si[8], nr_[8], ni_[8];
; #pragma unroll
;         for (int q = 0; q < 8; ++q) { const float* sp = S + ((size_t)g * CHPAD + chunk_of(q)) * 256 + d * 128 + p; sr[q] = sp[0]; si[q] = sp[64]; }
.LBB0_473:
	s_or_b64 exec, exec, s[0:1]
	v_mul_f32_e32 v2, 0x42000000, v2
	v_mul_f32_e32 v2, v2, v3
	v_mul_f32_e32 v3, 0x3fb8aa3b, v2
	v_fma_f32 v8, v2, s43, -v3
	v_rndne_f32_e32 v9, v3
	v_fmac_f32_e32 v8, 0x32a5705f, v2
	v_sub_f32_e32 v3, v3, v9
	v_add_f32_e32 v3, v3, v8
	v_cvt_i32_f32_e32 v8, v9
	v_exp_f32_e32 v3, v3
	v_cmp_ngt_f32_e32 vcc, s45, v2
	v_xor_b32_e32 v5, v5, v4
	s_brev_b32 s0, 1
	v_ldexp_f32 v3, v3, v8
	v_cndmask_b32_e32 v3, 0, v3, vcc
	v_cmp_nlt_f32_e32 vcc, s46, v2
	v_mul_f32_e32 v2, v6, v6
	v_fmamk_f32 v8, v2, 0xb94c1982, v228
	v_fmaak_f32 v8, v2, v8, 0xbe2aaa9d
	v_mul_f32_e32 v8, v2, v8
	v_fmac_f32_e32 v6, v6, v8
	v_fmamk_f32 v8, v2, 0x37d75334, v229
	v_fmaak_f32 v8, v2, v8, 0x3d2aabf7
	v_fmaak_f32 v8, v2, v8, 0xbf000004
	v_fma_f32 v2, v2, v8, 1.0
	v_lshlrev_b32_e32 v8, 30, v7
	v_and_b32_e32 v7, 1, v7
	v_cndmask_b32_e32 v3, v238, v3, vcc
	v_cmp_eq_u32_e32 vcc, 0, v7
	v_and_b32_e32 v9, 0x80000000, v8
	s_mul_i32 s33, s14, 0x500
	v_cndmask_b32_e32 v7, v2, v6, vcc
	v_xor_b32_e32 v5, v5, v7
	v_xor_b32_e32 v12, v5, v9
	v_xor_b32_e32 v5, 0x80000000, v6
	v_cndmask_b32_e32 v2, v5, v2, vcc
	v_bitop3_b32 v2, v2, v8, s0 bitop3:0x78
	s_movk_i32 s0, 0x1f8
	v_cmp_class_f32_e64 vcc, v4, s0
	s_lshl_b32 s0, s2, 7
	s_and_b32 s96, s0, 0x300
	s_lshr_b32 s0, s96, 5
	s_or_b32 s60, s0, 0x400
	s_or_b32 s0, s60, s25
	s_mul_hi_i32 s97, s14, 0x500
	s_add_u32 s20, s33, s0
	s_addc_u32 s21, s97, 0
	s_lshl_b64 s[0:1], s[20:21], 10
	v_lshl_add_u64 v[4:5], v[0:1], 0, s[0:1]
	s_or_b32 s0, s60, s28
	s_add_u32 s18, s33, s0
	s_addc_u32 s19, s97, 0
	s_lshl_b64 s[0:1], s[18:19], 10
	v_lshl_add_u64 v[6:7], v[0:1], 0, s[0:1]
	s_or_b32 s0, s60, s29
	s_add_u32 s14, s33, s0
	s_addc_u32 s15, s97, 0
	s_lshl_b64 s[0:1], s[14:15], 10
	v_lshl_add_u64 v[8:9], v[0:1], 0, s[0:1]
	s_or_b32 s0, s60, s26
	s_add_u32 s12, s33, s0
	s_addc_u32 s13, s97, 0
	s_lshl_b64 s[0:1], s[12:13], 10
	v_lshl_add_u64 v[10:11], v[0:1], 0, s[0:1]
	s_sub_i32 s0, s60, s22
	s_add_i32 s0, s0, 4
	s_add_u32 s16, s33, s0
	s_addc_u32 s17, s97, 0
	s_lshl_b64 s[0:1], s[16:17], 10
	global_load_dword v32, v[4:5], off
	global_load_dword v33, v[4:5], off offset:256
	global_load_dword v34, v[6:7], off
	global_load_dword v35, v[6:7], off offset:256
	global_load_dword v36, v[8:9], off
	global_load_dword v37, v[8:9], off offset:256
	global_load_dword v22, v[10:11], off
	global_load_dword v23, v[10:11], off offset:256
	v_lshl_add_u64 v[4:5], v[0:1], 0, s[0:1]
	s_or_b32 s0, s60, s30
	s_add_u32 s8, s33, s0
	s_addc_u32 s9, s97, 0
	s_lshl_b64 s[0:1], s[8:9], 10
	v_lshl_add_u64 v[6:7], v[0:1], 0, s[0:1]
	s_or_b32 s0, s60, s31
	s_add_u32 s6, s33, s0
	s_addc_u32 s7, s97, 0
	s_lshl_b64 s[0:1], s[6:7], 10
	v_lshl_add_u64 v[8:9], v[0:1], 0, s[0:1]
	s_or_b32 s0, s60, s34
	s_add_u32 s0, s33, s0
	s_addc_u32 s1, s97, 0
	s_lshl_b64 s[60:61], s[0:1], 10
	v_lshl_add_u64 v[10:11], v[0:1], 0, s[60:61]
	s_or_b32 s60, s96, s27
	s_add_u32 s60, s33, s60
	s_addc_u32 s61, s97, 0
	s_lshl_b64 s[60:61], s[60:61], 10
	global_load_dword v20, v[4:5], off
	global_load_dword v21, v[4:5], off offset:256
	global_load_dword v18, v[6:7], off
	global_load_dword v19, v[6:7], off offset:256
	global_load_dword v16, v[8:9], off
	global_load_dword v17, v[8:9], off offset:256
	global_load_dword v14, v[10:11], off
	global_load_dword v15, v[10:11], off offset:256
	v_lshl_add_u64 v[6:7], v[0:1], 0, s[60:61]
	s_or_b32 s60, s96, s35
	s_add_u32 s60, s33, s60
	s_addc_u32 s61, s97, 0
	s_lshl_b64 s[60:61], s[60:61], 10
	v_lshl_add_u64 v[8:9], v[0:1], 0, s[60:61]
	s_or_b32 s60, s96, s49
	s_add_u32 s60, s33, s60
	s_addc_u32 s61, s97, 0
	s_lshl_b64 s[60:61], s[60:61], 10
	v_lshl_add_u64 v[10:11], v[0:1], 0, s[60:61]
	s_or_b32 s60, s96, s50
	s_add_u32 s60, s33, s60
	s_addc_u32 s61, s97, 0
	s_lshl_b64 s[60:61], s[60:61], 10
	v_cndmask_b32_e32 v4, v241, v12, vcc
	v_lshl_add_u64 v[12:13], v[0:1], 0, s[60:61]
	s_or_b32 s60, s96, s51
	s_add_u32 s60, s33, s60
	s_addc_u32 s61, s97, 0
	s_lshl_b64 s[60:61], s[60:61], 10
	global_load_dword v30, v[6:7], off
	global_load_dword v31, v[6:7], off offset:256
	global_load_dword v28, v[8:9], off
	global_load_dword v29, v[8:9], off offset:256
	global_load_dword v26, v[10:11], off
	global_load_dword v27, v[10:11], off offset:256
	global_load_dword v24, v[12:13], off
	global_load_dword v25, v[12:13], off offset:256
	v_lshl_add_u64 v[6:7], v[0:1], 0, s[60:61]
	s_or_b32 s60, s96, s92
	s_add_u32 s60, s33, s60
	s_addc_u32 s61, s97, 0
	s_lshl_b64 s[60:61], s[60:61], 10
	v_lshl_add_u64 v[8:9], v[0:1], 0, s[60:61]
	s_or_b32 s60, s96, s94
	s_add_u32 s60, s33, s60
	s_addc_u32 s61, s97, 0
	s_lshl_b64 s[60:61], s[60:61], 10
	v_lshl_add_u64 v[38:39], v[0:1], 0, s[60:61]
	s_or_b32 s60, s96, s95
	s_add_u32 s60, s33, s60
	s_addc_u32 s61, s97, 0
	s_lshl_b64 s[60:61], s[60:61], 10
	v_lshl_add_u64 v[40:41], v[0:1], 0, s[60:61]
	global_load_dword v12, v[6:7], off
	global_load_dword v13, v[6:7], off offset:256
	global_load_dword v10, v[8:9], off
	global_load_dword v11, v[8:9], off offset:256
	s_nop 0
	global_load_dword v8, v[38:39], off
	global_load_dword v9, v[38:39], off offset:256
	global_load_dword v6, v[40:41], off
	global_load_dword v7, v[40:41], off offset:256
	s_mulk_i32 s21, 0x600
	s_mul_hi_u32 s60, s20, 0x600
	s_add_i32 s60, s60, s21
	s_mulk_i32 s20, 0x600
	s_add_u32 s21, s88, s20
	s_addc_u32 s61, s89, s60
	s_lshl_b32 s20, s24, 1
	s_add_u32 s60, s21, s20
	s_addc_u32 s61, s61, 0
	s_mulk_i32 s19, 0x600
	s_mul_hi_u32 s21, s18, 0x600
	v_lshl_add_u64 v[38:39], s[60:61], 0, v[192:193]
	s_add_i32 s21, s21, s19
	s_mulk_i32 s18, 0x600
	v_cndmask_b32_e32 v2, v241, v2, vcc
	v_lshl_add_u64 v[40:41], v[38:39], 0, s[4:5]
	v_add_co_u32_e32 v38, vcc, s39, v38
	s_add_u32 s18, s88, s18
	v_mul_f32_e32 v2, v3, v2
	v_mul_f32_e32 v4, v3, v4
	s_waitcnt vmcnt(0)
; __device__ __forceinline__ unsigned cvt_pk_bf16(float lo, float hi) { f32x2 v = {lo, hi}; bf16x2_t b = __builtin_convertvector(v, bf16x2_t); return __builtin_bit_cast(unsigned, b); }
; __device__ __forceinline__ void phase_scan(const Frame& F, const Params& P, int l) {
;     ...
;         const int ctxb = (NLAT + 256 * b) / 32, latb = 256 * b;
;         float cr = 0.f, ci = 0.f;
;         auto chunk_of = [&](int j) -> int { return (j < 8) ? (ctxb + (d ? 7 - j : j)) : (latb + (d ? 255 - (j - 8) : (j - 8))); };
;         float sr[8], si[8], nr_[8], ni_[8];
; #pragma unroll
;         for (int q = 0; q < 8; ++q) { const float* sp = S + ((size_t)g * CHPAD + chunk_of(q)) * 256 + d * 128 + p; sr[q] = sp[0]; si[q] = sp[64]; }
;         for (int j0 = 0; j0 < 264; j0 += 8) {
;             if (j0 + 8 < 264) {
; #pragma unroll
;                 for (int q = 0; q < 8; ++q) { const float* sp = S + ((size_t)g * CHPAD + chunk_of(j0 + 8 + q)) * 256 + d * 128 + p; nr_[q] = sp[0]; ni_[q] = sp[64]; }
;             }
; #pragma unroll
;             for (int q = 0; q < 8; ++q) {
;                 bf16_t* cp = UC + ((size_t)g * CHPAD + chunk_of(j0 + q)) * 768 + 512 + d * 128 + p;
;                 cp[0] = (bf16_t)(cvt_pk_bf16(cr, 0.f) & 0xffffu); cp[64] = (bf16_t)(cvt_pk_bf16(ci, 0.f) & 0xffffu);
;                 const float nr = aLr * cr - aLi * ci + sr[q], ni = aLr * ci + aLi * cr + si[q]; cr = nr; ci = ni;
	s_lshr_b32 s0, s2, 3
	s_mul_i32 s0, s0, 0x500
	s_lshr_b32 s1, s2, 1
	s_and_b32 s1, s1, 3
	s_lshl_b32 s6, s1, 3
	s_add_i32 s6, s6, 0x400
	s_mul_i32 s7, s22, 7
	s_add_i32 s6, s6, s7
	s_add_i32 s6, s6, s0
	s_lshl_b32 s1, s1, 8
	s_mul_i32 s7, s22, 0xff
	s_add_i32 s1, s1, s7
	s_add_i32 s1, s1, s0
	v_readlane_b32 s16, v251, 37
	v_readlane_b32 s17, v251, 38
	s_nop 3
	s_lshl_b32 s7, s6, 10
	s_add_u32 s12, s16, s7
	s_addc_u32 s13, s17, 0
	s_lshl_b32 s7, s1, 10
	s_add_u32 s8, s16, s7
	s_addc_u32 s9, s17, 0
	s_add_u32 s18, s88, 0x16100000
	s_addc_u32 s19, s89, 0
	s_mul_i32 s7, s6, 0x600
	s_add_u32 s14, s18, s7
	s_addc_u32 s15, s19, 0
	s_mul_i32 s7, s1, 0x600
	s_add_u32 s60, s18, s7
	s_addc_u32 s61, s19, 0
	s_lshl_b32 s7, s22, 11
	s_sub_i32 s16, 0x400, s7
	s_sub_i32 s17, 0, s22
	s_mul_i32 s7, s22, 0xc00
	s_sub_i32 s18, 0x600, s7
	s_sub_i32 s19, 0, s22
	s_lshl_b32 s7, s22, 9
	v_lshl_add_u32 v60, v194, 2, s7
	s_lshl_b32 s7, s22, 8
	v_lshl_add_u32 v61, v194, 1, s7
	v_mov_b32_e32 v54, 0
	v_mov_b32_e32 v55, 0
	global_load_dword v6, v60, s[12:13]
	global_load_dword v7, v60, s[12:13] offset:256
	s_add_u32 s12, s12, s16
	s_addc_u32 s13, s13, s17
	global_load_dword v8, v60, s[12:13]
	global_load_dword v9, v60, s[12:13] offset:256
	s_add_u32 s12, s12, s16
	s_addc_u32 s13, s13, s17
	global_load_dword v10, v60, s[12:13]
	global_load_dword v11, v60, s[12:13] offset:256
	s_add_u32 s12, s12, s16
	s_addc_u32 s13, s13, s17
	global_load_dword v12, v60, s[12:13]
	global_load_dword v13, v60, s[12:13] offset:256
	s_add_u32 s12, s12, s16
	s_addc_u32 s13, s13, s17
	global_load_dword v14, v60, s[12:13]
	global_load_dword v15, v60, s[12:13] offset:256
	s_add_u32 s12, s12, s16
	s_addc_u32 s13, s13, s17
	global_load_dword v16, v60, s[12:13]
	global_load_dword v17, v60, s[12:13] offset:256
	s_add_u32 s12, s12, s16
	s_addc_u32 s13, s13, s17
	global_load_dword v18, v60, s[12:13]
	global_load_dword v19, v60, s[12:13] offset:256
	s_add_u32 s12, s12, s16
	s_addc_u32 s13, s13, s17
	global_load_dword v20, v60, s[12:13]
	global_load_dword v21, v60, s[12:13] offset:256
	s_add_u32 s12, s12, s16
	s_addc_u32 s13, s13, s17
	s_mov_b64 s[12:13], s[8:9]
	global_load_dword v22, v60, s[12:13]
	global_load_dword v23, v60, s[12:13] offset:256
	s_add_u32 s12, s12, s16
	s_addc_u32 s13, s13, s17
	global_load_dword v24, v60, s[12:13]
	global_load_dword v25, v60, s[12:13] offset:256
	s_add_u32 s12, s12, s16
	s_addc_u32 s13, s13, s17
	global_load_dword v26, v60, s[12:13]
	global_load_dword v27, v60, s[12:13] offset:256
	s_add_u32 s12, s12, s16
	s_addc_u32 s13, s13, s17
	global_load_dword v28, v60, s[12:13]
	global_load_dword v29, v60, s[12:13] offset:256
	s_add_u32 s12, s12, s16
	s_addc_u32 s13, s13, s17
	global_load_dword v30, v60, s[12:13]
	global_load_dword v31, v60, s[12:13] offset:256
	s_add_u32 s12, s12, s16
	s_addc_u32 s13, s13, s17
	global_load_dword v32, v60, s[12:13]
	global_load_dword v33, v60, s[12:13] offset:256
	s_add_u32 s12, s12, s16
	s_addc_u32 s13, s13, s17
	global_load_dword v34, v60, s[12:13]
	global_load_dword v35, v60, s[12:13] offset:256
	s_add_u32 s12, s12, s16
	s_addc_u32 s13, s13, s17
	global_load_dword v36, v60, s[12:13]
	global_load_dword v37, v60, s[12:13] offset:256
	s_add_u32 s12, s12, s16
	s_addc_u32 s13, s13, s17
	s_waitcnt vmcnt(16)
	global_load_dword v38, v60, s[12:13]
	global_load_dword v39, v60, s[12:13] offset:256
	s_add_u32 s12, s12, s16
	s_addc_u32 s13, s13, s17
	global_load_dword v40, v60, s[12:13]
	global_load_dword v41, v60, s[12:13] offset:256
	s_add_u32 s12, s12, s16
	s_addc_u32 s13, s13, s17
	global_load_dword v42, v60, s[12:13]
	global_load_dword v43, v60, s[12:13] offset:256
	s_add_u32 s12, s12, s16
	s_addc_u32 s13, s13, s17
	global_load_dword v44, v60, s[12:13]
	global_load_dword v45, v60, s[12:13] offset:256
	s_add_u32 s12, s12, s16
	s_addc_u32 s13, s13, s17
	global_load_dword v46, v60, s[12:13]
	global_load_dword v47, v60, s[12:13] offset:256
	s_add_u32 s12, s12, s16
	s_addc_u32 s13, s13, s17
	global_load_dword v48, v60, s[12:13]
	global_load_dword v49, v60, s[12:13] offset:256
	s_add_u32 s12, s12, s16
	s_addc_u32 s13, s13, s17
	global_load_dword v50, v60, s[12:13]
	global_load_dword v51, v60, s[12:13] offset:256
	s_add_u32 s12, s12, s16
	s_addc_u32 s13, s13, s17
	global_load_dword v52, v60, s[12:13]
	global_load_dword v53, v60, s[12:13] offset:256
	s_add_u32 s12, s12, s16
	s_addc_u32 s13, s13, s17
	v_cvt_pk_bf16_f32 v56, v54, v54
	v_cvt_pk_bf16_f32 v57, v55, v55
	global_store_short v61, v56, s[14:15] offset:1024
	global_store_short v61, v57, s[14:15] offset:1152
	v_mul_f32_e32 v58, v4, v55
	v_mul_f32_e32 v59, v2, v55
	v_fmac_f32_e32 v59, v4, v54
	v_fma_f32 v58, v2, v54, -v58
	s_add_u32 s14, s14, s18
	s_addc_u32 s15, s15, s19
	v_add_f32_e32 v54, v58, v6
	v_add_f32_e32 v55, v59, v7
	v_cvt_pk_bf16_f32 v56, v54, v54
	v_cvt_pk_bf16_f32 v57, v55, v55
	global_store_short v61, v56, s[14:15] offset:1024
	global_store_short v61, v57, s[14:15] offset:1152
	v_mul_f32_e32 v58, v4, v55
	v_mul_f32_e32 v59, v2, v55
	v_fmac_f32_e32 v59, v4, v54
	v_fma_f32 v58, v2, v54, -v58
	s_add_u32 s14, s14, s18
	s_addc_u32 s15, s15, s19
	v_add_f32_e32 v54, v58, v8
	v_add_f32_e32 v55, v59, v9
	v_cvt_pk_bf16_f32 v56, v54, v54
	v_cvt_pk_bf16_f32 v57, v55, v55
	global_store_short v61, v56, s[14:15] offset:1024
	global_store_short v61, v57, s[14:15] offset:1152
	v_mul_f32_e32 v58, v4, v55
	v_mul_f32_e32 v59, v2, v55
	v_fmac_f32_e32 v59, v4, v54
	v_fma_f32 v58, v2, v54, -v58
	s_add_u32 s14, s14, s18
	s_addc_u32 s15, s15, s19
	v_add_f32_e32 v54, v58, v10
	v_add_f32_e32 v55, v59, v11
	v_cvt_pk_bf16_f32 v56, v54, v54
	v_cvt_pk_bf16_f32 v57, v55, v55
	global_store_short v61, v56, s[14:15] offset:1024
; __device__ __forceinline__ unsigned cvt_pk_bf16(float lo, float hi) { f32x2 v = {lo, hi}; bf16x2_t b = __builtin_convertvector(v, bf16x2_t); return __builtin_bit_cast(unsigned, b); }
; __device__ __forceinline__ void phase_scan(const Frame& F, const Params& P, int l) {
;     ...
;         for (int j0 = 0; j0 < 264; j0 += 8) {
;             if (j0 + 8 < 264) {
; #pragma unroll
;                 for (int q = 0; q < 8; ++q) { const float* sp = S + ((size_t)g * CHPAD + chunk_of(j0 + 8 + q)) * 256 + d * 128 + p; nr_[q] = sp[0]; ni_[q] = sp[64]; }
;             }
; #pragma unroll
;             for (int q = 0; q < 8; ++q) {
;                 bf16_t* cp = UC + ((size_t)g * CHPAD + chunk_of(j0 + q)) * 768 + 512 + d * 128 + p;
;                 cp[0] = (bf16_t)(cvt_pk_bf16(cr, 0.f) & 0xffffu); cp[64] = (bf16_t)(cvt_pk_bf16(ci, 0.f) & 0xffffu);
;                 const float nr = aLr * cr - aLi * ci + sr[q], ni = aLr * ci + aLi * cr + si[q]; cr = nr; ci = ni;
;             }
; #pragma unroll
;             for (int q = 0; q < 8; ++q) { sr[q] = nr_[q]; si[q] = ni_[q]; }
	global_store_short v61, v57, s[14:15] offset:1152
	v_mul_f32_e32 v58, v4, v55
	v_mul_f32_e32 v59, v2, v55
	v_fmac_f32_e32 v59, v4, v54
	v_fma_f32 v58, v2, v54, -v58
	s_add_u32 s14, s14, s18
	s_addc_u32 s15, s15, s19
	v_add_f32_e32 v54, v58, v12
	v_add_f32_e32 v55, v59, v13
	v_cvt_pk_bf16_f32 v56, v54, v54
	v_cvt_pk_bf16_f32 v57, v55, v55
	global_store_short v61, v56, s[14:15] offset:1024
	global_store_short v61, v57, s[14:15] offset:1152
	v_mul_f32_e32 v58, v4, v55
	v_mul_f32_e32 v59, v2, v55
	v_fmac_f32_e32 v59, v4, v54
	v_fma_f32 v58, v2, v54, -v58
	s_add_u32 s14, s14, s18
	s_addc_u32 s15, s15, s19
	v_add_f32_e32 v54, v58, v14
	v_add_f32_e32 v55, v59, v15
	v_cvt_pk_bf16_f32 v56, v54, v54
	v_cvt_pk_bf16_f32 v57, v55, v55
	global_store_short v61, v56, s[14:15] offset:1024
	global_store_short v61, v57, s[14:15] offset:1152
	v_mul_f32_e32 v58, v4, v55
	v_mul_f32_e32 v59, v2, v55
	v_fmac_f32_e32 v59, v4, v54
	v_fma_f32 v58, v2, v54, -v58
	s_add_u32 s14, s14, s18
	s_addc_u32 s15, s15, s19
	v_add_f32_e32 v54, v58, v16
	v_add_f32_e32 v55, v59, v17
	v_cvt_pk_bf16_f32 v56, v54, v54
	v_cvt_pk_bf16_f32 v57, v55, v55
	global_store_short v61, v56, s[14:15] offset:1024
	global_store_short v61, v57, s[14:15] offset:1152
	v_mul_f32_e32 v58, v4, v55
	v_mul_f32_e32 v59, v2, v55
	v_fmac_f32_e32 v59, v4, v54
	v_fma_f32 v58, v2, v54, -v58
	s_add_u32 s14, s14, s18
	s_addc_u32 s15, s15, s19
	v_add_f32_e32 v54, v58, v18
	v_add_f32_e32 v55, v59, v19
	v_cvt_pk_bf16_f32 v56, v54, v54
	v_cvt_pk_bf16_f32 v57, v55, v55
	global_store_short v61, v56, s[14:15] offset:1024
	global_store_short v61, v57, s[14:15] offset:1152
	v_mul_f32_e32 v58, v4, v55
	v_mul_f32_e32 v59, v2, v55
	v_fmac_f32_e32 v59, v4, v54
	v_fma_f32 v58, v2, v54, -v58
	s_add_u32 s14, s14, s18
	s_addc_u32 s15, s15, s19
	v_add_f32_e32 v54, v58, v20
	v_add_f32_e32 v55, v59, v21
	s_mov_b64 s[14:15], s[60:61]
	s_waitcnt vmcnt(32)
	global_load_dword v6, v60, s[12:13]
	global_load_dword v7, v60, s[12:13] offset:256
	s_add_u32 s12, s12, s16
	s_addc_u32 s13, s13, s17
	global_load_dword v8, v60, s[12:13]
	global_load_dword v9, v60, s[12:13] offset:256
	s_add_u32 s12, s12, s16
	s_addc_u32 s13, s13, s17
	global_load_dword v10, v60, s[12:13]
	global_load_dword v11, v60, s[12:13] offset:256
	s_add_u32 s12, s12, s16
	s_addc_u32 s13, s13, s17
	global_load_dword v12, v60, s[12:13]
	global_load_dword v13, v60, s[12:13] offset:256
	s_add_u32 s12, s12, s16
	s_addc_u32 s13, s13, s17
	global_load_dword v14, v60, s[12:13]
	global_load_dword v15, v60, s[12:13] offset:256
	s_add_u32 s12, s12, s16
	s_addc_u32 s13, s13, s17
	global_load_dword v16, v60, s[12:13]
	global_load_dword v17, v60, s[12:13] offset:256
	s_add_u32 s12, s12, s16
	s_addc_u32 s13, s13, s17
	global_load_dword v18, v60, s[12:13]
	global_load_dword v19, v60, s[12:13] offset:256
	s_add_u32 s12, s12, s16
	s_addc_u32 s13, s13, s17
	global_load_dword v20, v60, s[12:13]
	global_load_dword v21, v60, s[12:13] offset:256
	s_add_u32 s12, s12, s16
	s_addc_u32 s13, s13, s17
	v_cvt_pk_bf16_f32 v56, v54, v54
	v_cvt_pk_bf16_f32 v57, v55, v55
	global_store_short v61, v56, s[14:15] offset:1024
	global_store_short v61, v57, s[14:15] offset:1152
	v_mul_f32_e32 v58, v4, v55
	v_mul_f32_e32 v59, v2, v55
	v_fmac_f32_e32 v59, v4, v54
	v_fma_f32 v58, v2, v54, -v58
	s_add_u32 s14, s14, s18
	s_addc_u32 s15, s15, s19
	v_add_f32_e32 v54, v58, v22
	v_add_f32_e32 v55, v59, v23
	v_cvt_pk_bf16_f32 v56, v54, v54
	v_cvt_pk_bf16_f32 v57, v55, v55
	global_store_short v61, v56, s[14:15] offset:1024
	global_store_short v61, v57, s[14:15] offset:1152
	v_mul_f32_e32 v58, v4, v55
	v_mul_f32_e32 v59, v2, v55
	v_fmac_f32_e32 v59, v4, v54
	v_fma_f32 v58, v2, v54, -v58
	s_add_u32 s14, s14, s18
	s_addc_u32 s15, s15, s19
	v_add_f32_e32 v54, v58, v24
	v_add_f32_e32 v55, v59, v25
	v_cvt_pk_bf16_f32 v56, v54, v54
	v_cvt_pk_bf16_f32 v57, v55, v55
	global_store_short v61, v56, s[14:15] offset:1024
	global_store_short v61, v57, s[14:15] offset:1152
	v_mul_f32_e32 v58, v4, v55
	v_mul_f32_e32 v59, v2, v55
	v_fmac_f32_e32 v59, v4, v54
	v_fma_f32 v58, v2, v54, -v58
	s_add_u32 s14, s14, s18
	s_addc_u32 s15, s15, s19
	v_add_f32_e32 v54, v58, v26
	v_add_f32_e32 v55, v59, v27
	v_cvt_pk_bf16_f32 v56, v54, v54
	v_cvt_pk_bf16_f32 v57, v55, v55
	global_store_short v61, v56, s[14:15] offset:1024
	global_store_short v61, v57, s[14:15] offset:1152
	v_mul_f32_e32 v58, v4, v55
	v_mul_f32_e32 v59, v2, v55
	v_fmac_f32_e32 v59, v4, v54
	v_fma_f32 v58, v2, v54, -v58
	s_add_u32 s14, s14, s18
	s_addc_u32 s15, s15, s19
	v_add_f32_e32 v54, v58, v28
	v_add_f32_e32 v55, v59, v29
	v_cvt_pk_bf16_f32 v56, v54, v54
	v_cvt_pk_bf16_f32 v57, v55, v55
	global_store_short v61, v56, s[14:15] offset:1024
	global_store_short v61, v57, s[14:15] offset:1152
	v_mul_f32_e32 v58, v4, v55
	v_mul_f32_e32 v59, v2, v55
	v_fmac_f32_e32 v59, v4, v54
	v_fma_f32 v58, v2, v54, -v58
	s_add_u32 s14, s14, s18
	s_addc_u32 s15, s15, s19
	v_add_f32_e32 v54, v58, v30
	v_add_f32_e32 v55, v59, v31
	v_cvt_pk_bf16_f32 v56, v54, v54
	v_cvt_pk_bf16_f32 v57, v55, v55
	global_store_short v61, v56, s[14:15] offset:1024
	global_store_short v61, v57, s[14:15] offset:1152
	v_mul_f32_e32 v58, v4, v55
	v_mul_f32_e32 v59, v2, v55
	v_fmac_f32_e32 v59, v4, v54
	v_fma_f32 v58, v2, v54, -v58
	s_add_u32 s14, s14, s18
	s_addc_u32 s15, s15, s19
	v_add_f32_e32 v54, v58, v32
	v_add_f32_e32 v55, v59, v33
	v_cvt_pk_bf16_f32 v56, v54, v54
	v_cvt_pk_bf16_f32 v57, v55, v55
	global_store_short v61, v56, s[14:15] offset:1024
	global_store_short v61, v57, s[14:15] offset:1152
	v_mul_f32_e32 v58, v4, v55
	v_mul_f32_e32 v59, v2, v55
	v_fmac_f32_e32 v59, v4, v54
	v_fma_f32 v58, v2, v54, -v58
	s_add_u32 s14, s14, s18
	s_addc_u32 s15, s15, s19
	v_add_f32_e32 v54, v58, v34
	v_add_f32_e32 v55, v59, v35
	v_cvt_pk_bf16_f32 v56, v54, v54
	v_cvt_pk_bf16_f32 v57, v55, v55
	global_store_short v61, v56, s[14:15] offset:1024
	global_store_short v61, v57, s[14:15] offset:1152
	v_mul_f32_e32 v58, v4, v55
	v_mul_f32_e32 v59, v2, v55
	v_fmac_f32_e32 v59, v4, v54
	v_fma_f32 v58, v2, v54, -v58
	s_add_u32 s14, s14, s18
	s_addc_u32 s15, s15, s19
	v_add_f32_e32 v54, v58, v36
	v_add_f32_e32 v55, v59, v37
	s_waitcnt vmcnt(48)
; __device__ __forceinline__ unsigned cvt_pk_bf16(float lo, float hi) { f32x2 v = {lo, hi}; bf16x2_t b = __builtin_convertvector(v, bf16x2_t); return __builtin_bit_cast(unsigned, b); }
; __device__ __forceinline__ void phase_scan(const Frame& F, const Params& P, int l) {
;     ...
;         for (int j0 = 0; j0 < 264; j0 += 8) {
;             if (j0 + 8 < 264) {
; #pragma unroll
;                 for (int q = 0; q < 8; ++q) { const float* sp = S + ((size_t)g * CHPAD + chunk_of(j0 + 8 + q)) * 256 + d * 128 + p; nr_[q] = sp[0]; ni_[q] = sp[64]; }
;             }
; #pragma unroll
;             for (int q = 0; q < 8; ++q) {
;                 bf16_t* cp = UC + ((size_t)g * CHPAD + chunk_of(j0 + q)) * 768 + 512 + d * 128 + p;
;                 cp[0] = (bf16_t)(cvt_pk_bf16(cr, 0.f) & 0xffffu); cp[64] = (bf16_t)(cvt_pk_bf16(ci, 0.f) & 0xffffu);
;                 const float nr = aLr * cr - aLi * ci + sr[q], ni = aLr * ci + aLi * cr + si[q]; cr = nr; ci = ni;
;             }
; #pragma unroll
;             for (int q = 0; q < 8; ++q) { sr[q] = nr_[q]; si[q] = ni_[q]; }
	global_load_dword v22, v60, s[12:13]
	global_load_dword v23, v60, s[12:13] offset:256
	s_add_u32 s12, s12, s16
	s_addc_u32 s13, s13, s17
	global_load_dword v24, v60, s[12:13]
	global_load_dword v25, v60, s[12:13] offset:256
	s_add_u32 s12, s12, s16
	s_addc_u32 s13, s13, s17
	global_load_dword v26, v60, s[12:13]
	global_load_dword v27, v60, s[12:13] offset:256
	s_add_u32 s12, s12, s16
	s_addc_u32 s13, s13, s17
	global_load_dword v28, v60, s[12:13]
	global_load_dword v29, v60, s[12:13] offset:256
	s_add_u32 s12, s12, s16
	s_addc_u32 s13, s13, s17
	global_load_dword v30, v60, s[12:13]
	global_load_dword v31, v60, s[12:13] offset:256
	s_add_u32 s12, s12, s16
	s_addc_u32 s13, s13, s17
	global_load_dword v32, v60, s[12:13]
	global_load_dword v33, v60, s[12:13] offset:256
	s_add_u32 s12, s12, s16
	s_addc_u32 s13, s13, s17
	global_load_dword v34, v60, s[12:13]
	global_load_dword v35, v60, s[12:13] offset:256
	s_add_u32 s12, s12, s16
	s_addc_u32 s13, s13, s17
	global_load_dword v36, v60, s[12:13]
	global_load_dword v37, v60, s[12:13] offset:256
	s_add_u32 s12, s12, s16
	s_addc_u32 s13, s13, s17
	v_cvt_pk_bf16_f32 v56, v54, v54
	v_cvt_pk_bf16_f32 v57, v55, v55
	global_store_short v61, v56, s[14:15] offset:1024
	global_store_short v61, v57, s[14:15] offset:1152
	v_mul_f32_e32 v58, v4, v55
	v_mul_f32_e32 v59, v2, v55
	v_fmac_f32_e32 v59, v4, v54
	v_fma_f32 v58, v2, v54, -v58
	s_add_u32 s14, s14, s18
	s_addc_u32 s15, s15, s19
	v_add_f32_e32 v54, v58, v38
	v_add_f32_e32 v55, v59, v39
	v_cvt_pk_bf16_f32 v56, v54, v54
	v_cvt_pk_bf16_f32 v57, v55, v55
	global_store_short v61, v56, s[14:15] offset:1024
	global_store_short v61, v57, s[14:15] offset:1152
	v_mul_f32_e32 v58, v4, v55
	v_mul_f32_e32 v59, v2, v55
	v_fmac_f32_e32 v59, v4, v54
	v_fma_f32 v58, v2, v54, -v58
	s_add_u32 s14, s14, s18
	s_addc_u32 s15, s15, s19
	v_add_f32_e32 v54, v58, v40
	v_add_f32_e32 v55, v59, v41
	v_cvt_pk_bf16_f32 v56, v54, v54
	v_cvt_pk_bf16_f32 v57, v55, v55
	global_store_short v61, v56, s[14:15] offset:1024
	global_store_short v61, v57, s[14:15] offset:1152
	v_mul_f32_e32 v58, v4, v55
	v_mul_f32_e32 v59, v2, v55
	v_fmac_f32_e32 v59, v4, v54
	v_fma_f32 v58, v2, v54, -v58
	s_add_u32 s14, s14, s18
	s_addc_u32 s15, s15, s19
	v_add_f32_e32 v54, v58, v42
	v_add_f32_e32 v55, v59, v43
	v_cvt_pk_bf16_f32 v56, v54, v54
	v_cvt_pk_bf16_f32 v57, v55, v55
	global_store_short v61, v56, s[14:15] offset:1024
	global_store_short v61, v57, s[14:15] offset:1152
	v_mul_f32_e32 v58, v4, v55
	v_mul_f32_e32 v59, v2, v55
	v_fmac_f32_e32 v59, v4, v54
	v_fma_f32 v58, v2, v54, -v58
	s_add_u32 s14, s14, s18
	s_addc_u32 s15, s15, s19
	v_add_f32_e32 v54, v58, v44
	v_add_f32_e32 v55, v59, v45
	v_cvt_pk_bf16_f32 v56, v54, v54
	v_cvt_pk_bf16_f32 v57, v55, v55
	global_store_short v61, v56, s[14:15] offset:1024
	global_store_short v61, v57, s[14:15] offset:1152
	v_mul_f32_e32 v58, v4, v55
	v_mul_f32_e32 v59, v2, v55
	v_fmac_f32_e32 v59, v4, v54
	v_fma_f32 v58, v2, v54, -v58
	s_add_u32 s14, s14, s18
	s_addc_u32 s15, s15, s19
	v_add_f32_e32 v54, v58, v46
	v_add_f32_e32 v55, v59, v47
	v_cvt_pk_bf16_f32 v56, v54, v54
	v_cvt_pk_bf16_f32 v57, v55, v55
	global_store_short v61, v56, s[14:15] offset:1024
	global_store_short v61, v57, s[14:15] offset:1152
	v_mul_f32_e32 v58, v4, v55
	v_mul_f32_e32 v59, v2, v55
	v_fmac_f32_e32 v59, v4, v54
	v_fma_f32 v58, v2, v54, -v58
	s_add_u32 s14, s14, s18
	s_addc_u32 s15, s15, s19
	v_add_f32_e32 v54, v58, v48
	v_add_f32_e32 v55, v59, v49
	v_cvt_pk_bf16_f32 v56, v54, v54
	v_cvt_pk_bf16_f32 v57, v55, v55
	global_store_short v61, v56, s[14:15] offset:1024
	global_store_short v61, v57, s[14:15] offset:1152
	v_mul_f32_e32 v58, v4, v55
	v_mul_f32_e32 v59, v2, v55
	v_fmac_f32_e32 v59, v4, v54
	v_fma_f32 v58, v2, v54, -v58
	s_add_u32 s14, s14, s18
	s_addc_u32 s15, s15, s19
	v_add_f32_e32 v54, v58, v50
	v_add_f32_e32 v55, v59, v51
	v_cvt_pk_bf16_f32 v56, v54, v54
	v_cvt_pk_bf16_f32 v57, v55, v55
	global_store_short v61, v56, s[14:15] offset:1024
	global_store_short v61, v57, s[14:15] offset:1152
	v_mul_f32_e32 v58, v4, v55
	v_mul_f32_e32 v59, v2, v55
	v_fmac_f32_e32 v59, v4, v54
	v_fma_f32 v58, v2, v54, -v58
	s_add_u32 s14, s14, s18
	s_addc_u32 s15, s15, s19
	v_add_f32_e32 v54, v58, v52
	v_add_f32_e32 v55, v59, v53
	s_mov_b32 s20, 0
; __device__ __forceinline__ unsigned cvt_pk_bf16(float lo, float hi) { f32x2 v = {lo, hi}; bf16x2_t b = __builtin_convertvector(v, bf16x2_t); return __builtin_bit_cast(unsigned, b); }
; __device__ __forceinline__ void phase_scan(const Frame& F, const Params& P, int l) {
;     ...
;         for (int j0 = 0; j0 < 264; j0 += 8) {
;             if (j0 + 8 < 264) {
; #pragma unroll
;                 for (int q = 0; q < 8; ++q) { const float* sp = S + ((size_t)g * CHPAD + chunk_of(j0 + 8 + q)) * 256 + d * 128 + p; nr_[q] = sp[0]; ni_[q] = sp[64]; }
;             }
; #pragma unroll
;             for (int q = 0; q < 8; ++q) {
;                 bf16_t* cp = UC + ((size_t)g * CHPAD + chunk_of(j0 + q)) * 768 + 512 + d * 128 + p;
;                 cp[0] = (bf16_t)(cvt_pk_bf16(cr, 0.f) & 0xffffu); cp[64] = (bf16_t)(cvt_pk_bf16(ci, 0.f) & 0xffffu);
;                 const float nr = aLr * cr - aLi * ci + sr[q], ni = aLr * ci + aLi * cr + si[q]; cr = nr; ci = ni;
;             }
; #pragma unroll
;             for (int q = 0; q < 8; ++q) { sr[q] = nr_[q]; si[q] = ni_[q]; }
;         }
.Lscan_loop:
	s_waitcnt vmcnt(48)
	global_load_dword v38, v60, s[12:13]
	global_load_dword v39, v60, s[12:13] offset:256
	s_add_u32 s12, s12, s16
	s_addc_u32 s13, s13, s17
	global_load_dword v40, v60, s[12:13]
	global_load_dword v41, v60, s[12:13] offset:256
	s_add_u32 s12, s12, s16
	s_addc_u32 s13, s13, s17
	global_load_dword v42, v60, s[12:13]
	global_load_dword v43, v60, s[12:13] offset:256
	s_add_u32 s12, s12, s16
	s_addc_u32 s13, s13, s17
	global_load_dword v44, v60, s[12:13]
	global_load_dword v45, v60, s[12:13] offset:256
	s_add_u32 s12, s12, s16
	s_addc_u32 s13, s13, s17
	global_load_dword v46, v60, s[12:13]
	global_load_dword v47, v60, s[12:13] offset:256
	s_add_u32 s12, s12, s16
	s_addc_u32 s13, s13, s17
	global_load_dword v48, v60, s[12:13]
	global_load_dword v49, v60, s[12:13] offset:256
	s_add_u32 s12, s12, s16
	s_addc_u32 s13, s13, s17
	global_load_dword v50, v60, s[12:13]
	global_load_dword v51, v60, s[12:13] offset:256
	s_add_u32 s12, s12, s16
	s_addc_u32 s13, s13, s17
	global_load_dword v52, v60, s[12:13]
	global_load_dword v53, v60, s[12:13] offset:256
	s_add_u32 s12, s12, s16
	s_addc_u32 s13, s13, s17
	v_cvt_pk_bf16_f32 v56, v54, v54
	v_cvt_pk_bf16_f32 v57, v55, v55
	global_store_short v61, v56, s[14:15] offset:1024
	global_store_short v61, v57, s[14:15] offset:1152
	v_mul_f32_e32 v58, v4, v55
	v_mul_f32_e32 v59, v2, v55
	v_fmac_f32_e32 v59, v4, v54
	v_fma_f32 v58, v2, v54, -v58
	s_add_u32 s14, s14, s18
	s_addc_u32 s15, s15, s19
	v_add_f32_e32 v54, v58, v6
	v_add_f32_e32 v55, v59, v7
	v_cvt_pk_bf16_f32 v56, v54, v54
	v_cvt_pk_bf16_f32 v57, v55, v55
	global_store_short v61, v56, s[14:15] offset:1024
	global_store_short v61, v57, s[14:15] offset:1152
	v_mul_f32_e32 v58, v4, v55
	v_mul_f32_e32 v59, v2, v55
	v_fmac_f32_e32 v59, v4, v54
	v_fma_f32 v58, v2, v54, -v58
	s_add_u32 s14, s14, s18
	s_addc_u32 s15, s15, s19
	v_add_f32_e32 v54, v58, v8
	v_add_f32_e32 v55, v59, v9
	v_cvt_pk_bf16_f32 v56, v54, v54
	v_cvt_pk_bf16_f32 v57, v55, v55
	global_store_short v61, v56, s[14:15] offset:1024
	global_store_short v61, v57, s[14:15] offset:1152
	v_mul_f32_e32 v58, v4, v55
	v_mul_f32_e32 v59, v2, v55
	v_fmac_f32_e32 v59, v4, v54
	v_fma_f32 v58, v2, v54, -v58
	s_add_u32 s14, s14, s18
	s_addc_u32 s15, s15, s19
	v_add_f32_e32 v54, v58, v10
	v_add_f32_e32 v55, v59, v11
	v_cvt_pk_bf16_f32 v56, v54, v54
	v_cvt_pk_bf16_f32 v57, v55, v55
	global_store_short v61, v56, s[14:15] offset:1024
	global_store_short v61, v57, s[14:15] offset:1152
	v_mul_f32_e32 v58, v4, v55
	v_mul_f32_e32 v59, v2, v55
	v_fmac_f32_e32 v59, v4, v54
	v_fma_f32 v58, v2, v54, -v58
	s_add_u32 s14, s14, s18
	s_addc_u32 s15, s15, s19
	v_add_f32_e32 v54, v58, v12
	v_add_f32_e32 v55, v59, v13
	v_cvt_pk_bf16_f32 v56, v54, v54
	v_cvt_pk_bf16_f32 v57, v55, v55
	global_store_short v61, v56, s[14:15] offset:1024
	global_store_short v61, v57, s[14:15] offset:1152
	v_mul_f32_e32 v58, v4, v55
	v_mul_f32_e32 v59, v2, v55
	v_fmac_f32_e32 v59, v4, v54
	v_fma_f32 v58, v2, v54, -v58
	s_add_u32 s14, s14, s18
	s_addc_u32 s15, s15, s19
	v_add_f32_e32 v54, v58, v14
	v_add_f32_e32 v55, v59, v15
	v_cvt_pk_bf16_f32 v56, v54, v54
	v_cvt_pk_bf16_f32 v57, v55, v55
	global_store_short v61, v56, s[14:15] offset:1024
	global_store_short v61, v57, s[14:15] offset:1152
	v_mul_f32_e32 v58, v4, v55
	v_mul_f32_e32 v59, v2, v55
	v_fmac_f32_e32 v59, v4, v54
	v_fma_f32 v58, v2, v54, -v58
	s_add_u32 s14, s14, s18
	s_addc_u32 s15, s15, s19
	v_add_f32_e32 v54, v58, v16
	v_add_f32_e32 v55, v59, v17
	v_cvt_pk_bf16_f32 v56, v54, v54
	v_cvt_pk_bf16_f32 v57, v55, v55
	global_store_short v61, v56, s[14:15] offset:1024
	global_store_short v61, v57, s[14:15] offset:1152
	v_mul_f32_e32 v58, v4, v55
	v_mul_f32_e32 v59, v2, v55
	v_fmac_f32_e32 v59, v4, v54
	v_fma_f32 v58, v2, v54, -v58
	s_add_u32 s14, s14, s18
	s_addc_u32 s15, s15, s19
	v_add_f32_e32 v54, v58, v18
	v_add_f32_e32 v55, v59, v19
	v_cvt_pk_bf16_f32 v56, v54, v54
	v_cvt_pk_bf16_f32 v57, v55, v55
	global_store_short v61, v56, s[14:15] offset:1024
	global_store_short v61, v57, s[14:15] offset:1152
	v_mul_f32_e32 v58, v4, v55
	v_mul_f32_e32 v59, v2, v55
	v_fmac_f32_e32 v59, v4, v54
	v_fma_f32 v58, v2, v54, -v58
	s_add_u32 s14, s14, s18
	s_addc_u32 s15, s15, s19
	v_add_f32_e32 v54, v58, v20
	v_add_f32_e32 v55, v59, v21
	s_waitcnt vmcnt(48)
; __device__ __forceinline__ unsigned cvt_pk_bf16(float lo, float hi) { f32x2 v = {lo, hi}; bf16x2_t b = __builtin_convertvector(v, bf16x2_t); return __builtin_bit_cast(unsigned, b); }
; __device__ __forceinline__ void phase_scan(const Frame& F, const Params& P, int l) {
;     ...
;         for (int j0 = 0; j0 < 264; j0 += 8) {
;             if (j0 + 8 < 264) {
; #pragma unroll
;                 for (int q = 0; q < 8; ++q) { const float* sp = S + ((size_t)g * CHPAD + chunk_of(j0 + 8 + q)) * 256 + d * 128 + p; nr_[q] = sp[0]; ni_[q] = sp[64]; }
;             }
; #pragma unroll
;             for (int q = 0; q < 8; ++q) {
;                 bf16_t* cp = UC + ((size_t)g * CHPAD + chunk_of(j0 + q)) * 768 + 512 + d * 128 + p;
;                 cp[0] = (bf16_t)(cvt_pk_bf16(cr, 0.f) & 0xffffu); cp[64] = (bf16_t)(cvt_pk_bf16(ci, 0.f) & 0xffffu);
;                 const float nr = aLr * cr - aLi * ci + sr[q], ni = aLr * ci + aLi * cr + si[q]; cr = nr; ci = ni;
;             }
; #pragma unroll
;             for (int q = 0; q < 8; ++q) { sr[q] = nr_[q]; si[q] = ni_[q]; }
;         }
	global_load_dword v6, v60, s[12:13]
	global_load_dword v7, v60, s[12:13] offset:256
	s_add_u32 s12, s12, s16
	s_addc_u32 s13, s13, s17
	global_load_dword v8, v60, s[12:13]
	global_load_dword v9, v60, s[12:13] offset:256
	s_add_u32 s12, s12, s16
	s_addc_u32 s13, s13, s17
	global_load_dword v10, v60, s[12:13]
	global_load_dword v11, v60, s[12:13] offset:256
	s_add_u32 s12, s12, s16
	s_addc_u32 s13, s13, s17
	global_load_dword v12, v60, s[12:13]
	global_load_dword v13, v60, s[12:13] offset:256
	s_add_u32 s12, s12, s16
	s_addc_u32 s13, s13, s17
	global_load_dword v14, v60, s[12:13]
	global_load_dword v15, v60, s[12:13] offset:256
	s_add_u32 s12, s12, s16
	s_addc_u32 s13, s13, s17
	global_load_dword v16, v60, s[12:13]
	global_load_dword v17, v60, s[12:13] offset:256
	s_add_u32 s12, s12, s16
	s_addc_u32 s13, s13, s17
	global_load_dword v18, v60, s[12:13]
	global_load_dword v19, v60, s[12:13] offset:256
	s_add_u32 s12, s12, s16
	s_addc_u32 s13, s13, s17
	global_load_dword v20, v60, s[12:13]
	global_load_dword v21, v60, s[12:13] offset:256
	s_add_u32 s12, s12, s16
	s_addc_u32 s13, s13, s17
	v_cvt_pk_bf16_f32 v56, v54, v54
	v_cvt_pk_bf16_f32 v57, v55, v55
	global_store_short v61, v56, s[14:15] offset:1024
	global_store_short v61, v57, s[14:15] offset:1152
	v_mul_f32_e32 v58, v4, v55
	v_mul_f32_e32 v59, v2, v55
	v_fmac_f32_e32 v59, v4, v54
	v_fma_f32 v58, v2, v54, -v58
	s_add_u32 s14, s14, s18
	s_addc_u32 s15, s15, s19
	v_add_f32_e32 v54, v58, v22
	v_add_f32_e32 v55, v59, v23
	v_cvt_pk_bf16_f32 v56, v54, v54
	v_cvt_pk_bf16_f32 v57, v55, v55
	global_store_short v61, v56, s[14:15] offset:1024
	global_store_short v61, v57, s[14:15] offset:1152
	v_mul_f32_e32 v58, v4, v55
	v_mul_f32_e32 v59, v2, v55
	v_fmac_f32_e32 v59, v4, v54
	v_fma_f32 v58, v2, v54, -v58
	s_add_u32 s14, s14, s18
	s_addc_u32 s15, s15, s19
	v_add_f32_e32 v54, v58, v24
	v_add_f32_e32 v55, v59, v25
	v_cvt_pk_bf16_f32 v56, v54, v54
	v_cvt_pk_bf16_f32 v57, v55, v55
	global_store_short v61, v56, s[14:15] offset:1024
	global_store_short v61, v57, s[14:15] offset:1152
	v_mul_f32_e32 v58, v4, v55
	v_mul_f32_e32 v59, v2, v55
	v_fmac_f32_e32 v59, v4, v54
	v_fma_f32 v58, v2, v54, -v58
	s_add_u32 s14, s14, s18
	s_addc_u32 s15, s15, s19
	v_add_f32_e32 v54, v58, v26
	v_add_f32_e32 v55, v59, v27
	v_cvt_pk_bf16_f32 v56, v54, v54
	v_cvt_pk_bf16_f32 v57, v55, v55
	global_store_short v61, v56, s[14:15] offset:1024
	global_store_short v61, v57, s[14:15] offset:1152
	v_mul_f32_e32 v58, v4, v55
	v_mul_f32_e32 v59, v2, v55
	v_fmac_f32_e32 v59, v4, v54
	v_fma_f32 v58, v2, v54, -v58
	s_add_u32 s14, s14, s18
	s_addc_u32 s15, s15, s19
	v_add_f32_e32 v54, v58, v28
	v_add_f32_e32 v55, v59, v29
	v_cvt_pk_bf16_f32 v56, v54, v54
	v_cvt_pk_bf16_f32 v57, v55, v55
	global_store_short v61, v56, s[14:15] offset:1024
	global_store_short v61, v57, s[14:15] offset:1152
	v_mul_f32_e32 v58, v4, v55
	v_mul_f32_e32 v59, v2, v55
	v_fmac_f32_e32 v59, v4, v54
	v_fma_f32 v58, v2, v54, -v58
	s_add_u32 s14, s14, s18
	s_addc_u32 s15, s15, s19
	v_add_f32_e32 v54, v58, v30
	v_add_f32_e32 v55, v59, v31
	v_cvt_pk_bf16_f32 v56, v54, v54
	v_cvt_pk_bf16_f32 v57, v55, v55
	global_store_short v61, v56, s[14:15] offset:1024
	global_store_short v61, v57, s[14:15] offset:1152
	v_mul_f32_e32 v58, v4, v55
	v_mul_f32_e32 v59, v2, v55
	v_fmac_f32_e32 v59, v4, v54
	v_fma_f32 v58, v2, v54, -v58
	s_add_u32 s14, s14, s18
	s_addc_u32 s15, s15, s19
	v_add_f32_e32 v54, v58, v32
	v_add_f32_e32 v55, v59, v33
	v_cvt_pk_bf16_f32 v56, v54, v54
	v_cvt_pk_bf16_f32 v57, v55, v55
	global_store_short v61, v56, s[14:15] offset:1024
	global_store_short v61, v57, s[14:15] offset:1152
	v_mul_f32_e32 v58, v4, v55
	v_mul_f32_e32 v59, v2, v55
	v_fmac_f32_e32 v59, v4, v54
	v_fma_f32 v58, v2, v54, -v58
	s_add_u32 s14, s14, s18
	s_addc_u32 s15, s15, s19
	v_add_f32_e32 v54, v58, v34
	v_add_f32_e32 v55, v59, v35
	v_cvt_pk_bf16_f32 v56, v54, v54
	v_cvt_pk_bf16_f32 v57, v55, v55
	global_store_short v61, v56, s[14:15] offset:1024
	global_store_short v61, v57, s[14:15] offset:1152
	v_mul_f32_e32 v58, v4, v55
	v_mul_f32_e32 v59, v2, v55
	v_fmac_f32_e32 v59, v4, v54
	v_fma_f32 v58, v2, v54, -v58
	s_add_u32 s14, s14, s18
	s_addc_u32 s15, s15, s19
	v_add_f32_e32 v54, v58, v36
	v_add_f32_e32 v55, v59, v37
	s_waitcnt vmcnt(48)
; __device__ __forceinline__ unsigned cvt_pk_bf16(float lo, float hi) { f32x2 v = {lo, hi}; bf16x2_t b = __builtin_convertvector(v, bf16x2_t); return __builtin_bit_cast(unsigned, b); }
; __device__ __forceinline__ void phase_scan(const Frame& F, const Params& P, int l) {
;     ...
;         for (int j0 = 0; j0 < 264; j0 += 8) {
;             if (j0 + 8 < 264) {
; #pragma unroll
;                 for (int q = 0; q < 8; ++q) { const float* sp = S + ((size_t)g * CHPAD + chunk_of(j0 + 8 + q)) * 256 + d * 128 + p; nr_[q] = sp[0]; ni_[q] = sp[64]; }
;             }
; #pragma unroll
;             for (int q = 0; q < 8; ++q) {
;                 bf16_t* cp = UC + ((size_t)g * CHPAD + chunk_of(j0 + q)) * 768 + 512 + d * 128 + p;
;                 cp[0] = (bf16_t)(cvt_pk_bf16(cr, 0.f) & 0xffffu); cp[64] = (bf16_t)(cvt_pk_bf16(ci, 0.f) & 0xffffu);
;                 const float nr = aLr * cr - aLi * ci + sr[q], ni = aLr * ci + aLi * cr + si[q]; cr = nr; ci = ni;
;             }
; #pragma unroll
;             for (int q = 0; q < 8; ++q) { sr[q] = nr_[q]; si[q] = ni_[q]; }
;         }
;     }
	global_load_dword v22, v60, s[12:13]
	global_load_dword v23, v60, s[12:13] offset:256
	s_add_u32 s12, s12, s16
	s_addc_u32 s13, s13, s17
	global_load_dword v24, v60, s[12:13]
	global_load_dword v25, v60, s[12:13] offset:256
	s_add_u32 s12, s12, s16
	s_addc_u32 s13, s13, s17
	global_load_dword v26, v60, s[12:13]
	global_load_dword v27, v60, s[12:13] offset:256
	s_add_u32 s12, s12, s16
	s_addc_u32 s13, s13, s17
	global_load_dword v28, v60, s[12:13]
	global_load_dword v29, v60, s[12:13] offset:256
	s_add_u32 s12, s12, s16
	s_addc_u32 s13, s13, s17
	global_load_dword v30, v60, s[12:13]
	global_load_dword v31, v60, s[12:13] offset:256
	s_add_u32 s12, s12, s16
	s_addc_u32 s13, s13, s17
	global_load_dword v32, v60, s[12:13]
	global_load_dword v33, v60, s[12:13] offset:256
	s_add_u32 s12, s12, s16
	s_addc_u32 s13, s13, s17
	global_load_dword v34, v60, s[12:13]
	global_load_dword v35, v60, s[12:13] offset:256
	s_add_u32 s12, s12, s16
	s_addc_u32 s13, s13, s17
	global_load_dword v36, v60, s[12:13]
	global_load_dword v37, v60, s[12:13] offset:256
	s_add_u32 s12, s12, s16
	s_addc_u32 s13, s13, s17
	v_cvt_pk_bf16_f32 v56, v54, v54
	v_cvt_pk_bf16_f32 v57, v55, v55
	global_store_short v61, v56, s[14:15] offset:1024
	global_store_short v61, v57, s[14:15] offset:1152
	v_mul_f32_e32 v58, v4, v55
	v_mul_f32_e32 v59, v2, v55
	v_fmac_f32_e32 v59, v4, v54
	v_fma_f32 v58, v2, v54, -v58
	s_add_u32 s14, s14, s18
	s_addc_u32 s15, s15, s19
	v_add_f32_e32 v54, v58, v38
	v_add_f32_e32 v55, v59, v39
	v_cvt_pk_bf16_f32 v56, v54, v54
	v_cvt_pk_bf16_f32 v57, v55, v55
	global_store_short v61, v56, s[14:15] offset:1024
	global_store_short v61, v57, s[14:15] offset:1152
	v_mul_f32_e32 v58, v4, v55
	v_mul_f32_e32 v59, v2, v55
	v_fmac_f32_e32 v59, v4, v54
	v_fma_f32 v58, v2, v54, -v58
	s_add_u32 s14, s14, s18
	s_addc_u32 s15, s15, s19
	v_add_f32_e32 v54, v58, v40
	v_add_f32_e32 v55, v59, v41
	v_cvt_pk_bf16_f32 v56, v54, v54
	v_cvt_pk_bf16_f32 v57, v55, v55
	global_store_short v61, v56, s[14:15] offset:1024
	global_store_short v61, v57, s[14:15] offset:1152
	v_mul_f32_e32 v58, v4, v55
	v_mul_f32_e32 v59, v2, v55
	v_fmac_f32_e32 v59, v4, v54
	v_fma_f32 v58, v2, v54, -v58
	s_add_u32 s14, s14, s18
	s_addc_u32 s15, s15, s19
	v_add_f32_e32 v54, v58, v42
	v_add_f32_e32 v55, v59, v43
	v_cvt_pk_bf16_f32 v56, v54, v54
	v_cvt_pk_bf16_f32 v57, v55, v55
	global_store_short v61, v56, s[14:15] offset:1024
	global_store_short v61, v57, s[14:15] offset:1152
	v_mul_f32_e32 v58, v4, v55
	v_mul_f32_e32 v59, v2, v55
	v_fmac_f32_e32 v59, v4, v54
	v_fma_f32 v58, v2, v54, -v58
	s_add_u32 s14, s14, s18
	s_addc_u32 s15, s15, s19
	v_add_f32_e32 v54, v58, v44
	v_add_f32_e32 v55, v59, v45
	v_cvt_pk_bf16_f32 v56, v54, v54
	v_cvt_pk_bf16_f32 v57, v55, v55
	global_store_short v61, v56, s[14:15] offset:1024
	global_store_short v61, v57, s[14:15] offset:1152
	v_mul_f32_e32 v58, v4, v55
	v_mul_f32_e32 v59, v2, v55
	v_fmac_f32_e32 v59, v4, v54
	v_fma_f32 v58, v2, v54, -v58
	s_add_u32 s14, s14, s18
	s_addc_u32 s15, s15, s19
	v_add_f32_e32 v54, v58, v46
	v_add_f32_e32 v55, v59, v47
	v_cvt_pk_bf16_f32 v56, v54, v54
	v_cvt_pk_bf16_f32 v57, v55, v55
	global_store_short v61, v56, s[14:15] offset:1024
	global_store_short v61, v57, s[14:15] offset:1152
	v_mul_f32_e32 v58, v4, v55
	v_mul_f32_e32 v59, v2, v55
	v_fmac_f32_e32 v59, v4, v54
	v_fma_f32 v58, v2, v54, -v58
	s_add_u32 s14, s14, s18
	s_addc_u32 s15, s15, s19
	v_add_f32_e32 v54, v58, v48
	v_add_f32_e32 v55, v59, v49
	v_cvt_pk_bf16_f32 v56, v54, v54
	v_cvt_pk_bf16_f32 v57, v55, v55
	global_store_short v61, v56, s[14:15] offset:1024
	global_store_short v61, v57, s[14:15] offset:1152
	v_mul_f32_e32 v58, v4, v55
	v_mul_f32_e32 v59, v2, v55
	v_fmac_f32_e32 v59, v4, v54
	v_fma_f32 v58, v2, v54, -v58
	s_add_u32 s14, s14, s18
	s_addc_u32 s15, s15, s19
	v_add_f32_e32 v54, v58, v50
	v_add_f32_e32 v55, v59, v51
	v_cvt_pk_bf16_f32 v56, v54, v54
	v_cvt_pk_bf16_f32 v57, v55, v55
	global_store_short v61, v56, s[14:15] offset:1024
	global_store_short v61, v57, s[14:15] offset:1152
	v_mul_f32_e32 v58, v4, v55
	v_mul_f32_e32 v59, v2, v55
	v_fmac_f32_e32 v59, v4, v54
	v_fma_f32 v58, v2, v54, -v58
	s_add_u32 s14, s14, s18
	s_addc_u32 s15, s15, s19
	v_add_f32_e32 v54, v58, v52
	v_add_f32_e32 v55, v59, v53
	s_add_i32 s20, s20, 1
	s_cmp_lt_u32 s20, 10
	s_cbranch_scc1 .Lscan_loop
	s_waitcnt vmcnt(0)
	s_branch .LBB0_468
